# v58 plus 64-byte alignment of the four GEMM/attention loop heads and no L2 write-back at the barrier before prep
# baseline (speedup 1.0000x reference)
.Lbar_global:
	v_mov_b32_e32 v9, v3
	s_mov_b64 s[4:5], exec
	v_readlane_b32 s6, v255, 40
	s_cmp_eq_u32 s6, 1
	s_cbranch_scc0 .Lgl_wb
	s_mul_hi_u32 s6, s17, 0x1999999a
	s_mul_i32 s6, s6, 10
	s_sub_i32 s6, s17, s6
	s_cmp_eq_u32 s6, 3
	s_cbranch_scc1 .Lgl_nowb
